# P10 rope epilogue: rope-table/rstd loads issued 3 rows ahead into dead fragment registers with counted vmcnt (stores stay in flight); pk_mul+add -> mul+fma
# baseline (speedup 1.0000x reference)
.LBB0_1014:
	s_lshl_b32 s6, s6, 8
	s_add_i32 s6, s6, s90
	v_add_u32_e32 v140, s6, v182
	v_ashrrev_i32_e32 v141, 31, v140
	v_lshlrev_b32_e32 v132, 6, v140
	v_lshl_add_u64 v[142:143], v[140:141], 2, s[24:25]
	v_and_b32_e32 v190, 0x3ffc0, v132
	v_add_u32_e32 v192, 0, v140
	v_lshlrev_b32_e32 v192, 6, v192
	v_and_b32_e32 v192, 0x3ffc0, v192
	global_load_dword v193, v[142:143], off
	global_load_dwordx4 v[194:197], v192, s[22:23] offset:32
	global_load_dwordx4 v[198:201], v192, s[22:23]
	global_load_dwordx4 v[202:205], v192, s[22:23] offset:48
	global_load_dwordx4 v[206:209], v192, s[22:23] offset:16
	v_add_u32_e32 v210, 16, v140
	v_lshlrev_b32_e32 v210, 6, v210
	v_and_b32_e32 v210, 0x3ffc0, v210
	global_load_dword v211, v[142:143], off offset:64
	global_load_dwordx4 v[212:215], v210, s[22:23] offset:32
	global_load_dwordx4 v[216:219], v210, s[22:23]
	global_load_dwordx4 v[220:223], v210, s[22:23] offset:48
	global_load_dwordx4 v[224:227], v210, s[22:23] offset:16
	v_add_u32_e32 v228, 32, v140
	v_lshlrev_b32_e32 v228, 6, v228
	v_and_b32_e32 v228, 0x3ffc0, v228
	global_load_dword v229, v[142:143], off offset:128
	global_load_dwordx4 v[230:233], v228, s[22:23] offset:32
	global_load_dwordx4 v[234:237], v228, s[22:23]
	global_load_dwordx4 v[238:241], v228, s[22:23] offset:48
	global_load_dwordx4 v[242:245], v228, s[22:23] offset:16
	v_and_b32_e32 v145, 64, v180
	s_add_i32 s6, s7, s91
	v_xor_b32_e32 v132, 16, v180
	v_add_u32_e32 v155, 64, v145
	v_lshl_add_u32 v144, v181, 3, s6
	v_cmp_lt_i32_e64 s[6:7], v132, v155
	s_and_b64 s[62:63], s[38:39], s[66:67]
	s_nop 0
	v_cndmask_b32_e64 v132, v180, v132, s[6:7]
	v_lshlrev_b32_e32 v132, 2, v132
	ds_bpermute_b32 v155, v132, v120
	ds_bpermute_b32 v168, v132, v126
	ds_bpermute_b32 v157, v132, v121
	ds_bpermute_b32 v159, v132, v122
	ds_bpermute_b32 v161, v132, v123
	ds_bpermute_b32 v165, v132, v125
	v_mad_i64_i32 v[166:167], s[6:7], s60, v140, 0
	ds_bpermute_b32 v163, v132, v124
	v_cmp_eq_u32_e64 s[6:7], 0, v181
	v_cmp_gt_i32_e32 vcc, 2, v181
	s_waitcnt lgkmcnt(0)
	v_cndmask_b32_e64 v169, v155, -v155, s[6:7]
	v_cndmask_b32_e64 v189, v168, -v168, s[6:7]
	v_cndmask_b32_e64 v171, v157, -v157, s[6:7]
	ds_bpermute_b32 v191, v132, v127
	v_cndmask_b32_e64 v173, v159, -v159, s[6:7]
	v_cndmask_b32_e64 v183, v161, -v161, s[6:7]
	v_cndmask_b32_e64 v187, v165, -v165, s[6:7]
	s_and_b64 vcc, s[62:63], vcc
	v_ashrrev_i32_e32 v145, 31, v144
	v_cndmask_b32_e64 v185, v163, -v163, s[6:7]
	v_lshl_add_u64 v[144:145], v[144:145], 1, s[64:65]
	v_lshl_add_u64 v[166:167], v[166:167], 1, v[144:145]
	s_waitcnt vmcnt(10)
	v_mul_f32_e32 v141, s53, v193
	v_mov_b32_e32 v168, v198
	v_mov_b32_e32 v170, v199
	v_mov_b32_e32 v184, v198
	v_mov_b32_e32 v186, v199
	v_mul_f32_e32 v150, v194, v169
	v_mov_b32_e32 v159, v196
	v_mov_b32_e32 v165, v196
	v_mul_f32_e32 v154, v195, v171
	v_fma_f32 v148, v120, v168, v150
	v_mov_b32_e32 v163, v194
	v_mov_b32_e32 v188, v200
	v_mul_f32_e32 v156, v159, v173
	v_mul_f32_e32 v158, v197, v183
	v_fma_f32 v150, v121, v170, v154
	v_cndmask_b32_e32 v120, v120, v148, vcc
	v_mul_f32_e32 v160, v163, v185
	v_mul_f32_e32 v146, v195, v187
	v_mul_f32_e32 v162, v165, v189
	v_fma_f32 v151, v122, v200, v156
	v_fma_f32 v152, v123, v201, v158
	v_cndmask_b32_e32 v121, v121, v150, vcc
	v_mul_f32_e32 v120, v141, v120
	v_fma_f32 v146, v125, v186, v146
	v_fma_f32 v147, v126, v188, v162
	v_cndmask_b32_e32 v122, v122, v151, vcc
	v_cndmask_b32_e32 v123, v123, v152, vcc
	v_mul_f32_e32 v121, v141, v121
	v_cvt_pk_bf16_f32 v120, v120, v121
	v_mul_f32_e32 v122, v141, v122
	v_mul_f32_e32 v123, v141, v123
	v_cvt_pk_bf16_f32 v121, v122, v123
	global_store_dwordx2 v[166:167], v[120:121], off
	v_cndmask_b32_e32 v120, v126, v147, vcc
	v_mul_f32_e32 v122, v141, v120
	s_waitcnt lgkmcnt(0)
	v_cndmask_b32_e64 v121, v191, -v191, s[6:7]
	v_mul_f32_e32 v120, v197, v121
	v_fma_f32 v154, v124, v184, v160
	v_fma_f32 v120, v127, v201, v120
	v_cndmask_b32_e32 v120, v127, v120, vcc
	v_cndmask_b32_e32 v124, v124, v154, vcc
	v_cndmask_b32_e32 v125, v125, v146, vcc
	v_mul_f32_e32 v121, v141, v120
	v_mul_f32_e32 v124, v141, v124
	v_mul_f32_e32 v125, v141, v125
	v_cvt_pk_bf16_f32 v120, v124, v125
	v_cvt_pk_bf16_f32 v121, v122, v121
	global_store_dwordx2 v[166:167], v[120:121], off offset:256
	s_nop 0
	ds_bpermute_b32 v147, v132, v112
	ds_bpermute_b32 v149, v132, v113
	ds_bpermute_b32 v158, v132, v118
	ds_bpermute_b32 v160, v132, v119
	ds_bpermute_b32 v151, v132, v114
	ds_bpermute_b32 v153, v132, v115
	ds_bpermute_b32 v155, v132, v116
	ds_bpermute_b32 v157, v132, v117
	s_waitcnt lgkmcnt(7)
	v_cndmask_b32_e64 v159, v147, -v147, s[6:7]
	s_waitcnt lgkmcnt(6)
	v_cndmask_b32_e64 v161, v149, -v149, s[6:7]
	s_waitcnt lgkmcnt(5)
	v_cndmask_b32_e64 v173, v158, -v158, s[6:7]
	s_waitcnt lgkmcnt(4)
	v_cndmask_b32_e64 v183, v160, -v160, s[6:7]
	s_waitcnt lgkmcnt(3)
	v_cndmask_b32_e64 v163, v151, -v151, s[6:7]
	s_waitcnt lgkmcnt(2)
	v_cndmask_b32_e64 v165, v153, -v153, s[6:7]
	s_waitcnt lgkmcnt(1)
	v_cndmask_b32_e64 v169, v155, -v155, s[6:7]
	s_waitcnt lgkmcnt(0)
	v_cndmask_b32_e64 v171, v157, -v157, s[6:7]
	v_mov_b32_e32 v147, v202
	v_mov_b32_e32 v158, v206
	v_mov_b32_e32 v160, v207
	v_mov_b32_e32 v151, v204
	v_mov_b32_e32 v162, v208
	v_mov_b32_e32 v153, v205
	v_mov_b32_e32 v164, v209
	v_mov_b32_e32 v168, v206
	v_mov_b32_e32 v170, v207
	v_mov_b32_e32 v172, v208
	v_mov_b32_e32 v182, v209
	v_mul_f32_e32 v124, v147, v159
	v_mul_f32_e32 v126, v203, v161
	v_mov_b32_e32 v155, v202
	v_mov_b32_e32 v157, v204
	v_mul_f32_e32 v146, v151, v163
	v_mul_f32_e32 v148, v153, v165
	v_fma_f32 v124, v112, v158, v124
	v_fma_f32 v125, v113, v160, v126
	v_mul_f32_e32 v150, v155, v169
	v_mul_f32_e32 v120, v203, v171
	v_mul_f32_e32 v152, v157, v173
	v_mul_f32_e32 v122, v205, v183
	v_fma_f32 v126, v114, v162, v146
	v_fma_f32 v127, v115, v164, v148
	v_cndmask_b32_e32 v112, v112, v124, vcc
	v_cndmask_b32_e32 v113, v113, v125, vcc
	v_fma_f32 v146, v116, v168, v150
	v_fma_f32 v120, v117, v170, v120
	v_fma_f32 v121, v118, v172, v152
	v_fma_f32 v122, v119, v182, v122
	v_cndmask_b32_e32 v114, v114, v126, vcc
	v_cndmask_b32_e32 v115, v115, v127, vcc
	v_mul_f32_e32 v112, v141, v112
	v_mul_f32_e32 v113, v141, v113
	v_cndmask_b32_e32 v116, v116, v146, vcc
	v_cndmask_b32_e32 v117, v117, v120, vcc
	v_cndmask_b32_e32 v118, v118, v121, vcc
	v_cndmask_b32_e32 v119, v119, v122, vcc
	v_mul_f32_e32 v114, v141, v114
	v_mul_f32_e32 v115, v141, v115
	v_cvt_pk_bf16_f32 v112, v112, v113
	v_cvt_pk_bf16_f32 v113, v114, v115
	v_mul_f32_e32 v116, v141, v116
	v_mul_f32_e32 v117, v141, v117
	v_mul_f32_e32 v118, v141, v118
	v_mul_f32_e32 v119, v141, v119
	global_store_dwordx2 v[166:167], v[112:113], off offset:8
	v_cvt_pk_bf16_f32 v112, v116, v117
	v_cvt_pk_bf16_f32 v113, v118, v119
	global_store_dwordx2 v[166:167], v[112:113], off offset:264
	v_add_u32_e32 v192, 48, v140
	v_lshlrev_b32_e32 v192, 6, v192
	v_and_b32_e32 v192, 0x3ffc0, v192
	global_load_dword v193, v[142:143], off offset:192
	global_load_dwordx4 v[194:197], v192, s[22:23] offset:32
	global_load_dwordx4 v[198:201], v192, s[22:23]
	global_load_dwordx4 v[202:205], v192, s[22:23] offset:48
	global_load_dwordx4 v[206:209], v192, s[22:23] offset:16
	v_add_u32_e32 v121, 16, v140
	v_lshlrev_b32_e32 v112, 6, v121
	v_and_b32_e32 v141, 0x3ffc0, v112
	ds_bpermute_b32 v125, v132, v104
	ds_bpermute_b32 v127, v132, v105
	ds_bpermute_b32 v152, v132, v108
	ds_bpermute_b32 v154, v132, v109
	ds_bpermute_b32 v147, v132, v106
	ds_bpermute_b32 v149, v132, v107
	ds_bpermute_b32 v156, v132, v110
	ds_bpermute_b32 v158, v132, v111
	v_mad_i64_i32 v[150:151], s[62:63], s60, v121, 0
	s_waitcnt lgkmcnt(7)
	v_cndmask_b32_e64 v153, v125, -v125, s[6:7]
	s_waitcnt lgkmcnt(6)
	v_cndmask_b32_e64 v155, v127, -v127, s[6:7]
	s_waitcnt lgkmcnt(5)
	v_cndmask_b32_e64 v161, v152, -v152, s[6:7]
	s_waitcnt lgkmcnt(4)
	v_cndmask_b32_e64 v163, v154, -v154, s[6:7]
	s_waitcnt lgkmcnt(3)
	v_cndmask_b32_e64 v157, v147, -v147, s[6:7]
	s_waitcnt lgkmcnt(2)
	v_cndmask_b32_e64 v159, v149, -v149, s[6:7]
	s_waitcnt lgkmcnt(1)
	v_cndmask_b32_e64 v165, v156, -v156, s[6:7]
	s_waitcnt lgkmcnt(0)
	v_cndmask_b32_e64 v167, v158, -v158, s[6:7]
	v_lshl_add_u64 v[150:151], v[150:151], 1, v[144:145]
	s_waitcnt vmcnt(14)
	v_mul_f32_e32 v168, s53, v211
	v_mov_b32_e32 v121, v212
	v_mov_b32_e32 v152, v216
	v_mov_b32_e32 v154, v217
	v_mov_b32_e32 v125, v214
	v_mov_b32_e32 v156, v218
	v_mov_b32_e32 v127, v215
	v_mov_b32_e32 v158, v219
	v_mov_b32_e32 v160, v216
	v_mov_b32_e32 v162, v217
	v_mov_b32_e32 v164, v218
	v_mov_b32_e32 v166, v219
	v_mul_f32_e32 v116, v121, v153
	v_mul_f32_e32 v118, v213, v155
	v_mov_b32_e32 v147, v212
	v_mov_b32_e32 v149, v214
	v_mul_f32_e32 v120, v125, v157
	v_mul_f32_e32 v122, v127, v159
	v_fma_f32 v116, v104, v152, v116
	v_fma_f32 v117, v105, v154, v118
	v_mul_f32_e32 v124, v147, v161
	v_mul_f32_e32 v112, v213, v163
	v_mul_f32_e32 v126, v149, v165
	v_mul_f32_e32 v114, v215, v167
	v_fma_f32 v118, v106, v156, v120
	v_fma_f32 v119, v107, v158, v122
	v_cndmask_b32_e32 v104, v104, v116, vcc
	v_cndmask_b32_e32 v105, v105, v117, vcc
	v_fma_f32 v120, v108, v160, v124
	v_fma_f32 v112, v109, v162, v112
	v_fma_f32 v113, v110, v164, v126
	v_fma_f32 v114, v111, v166, v114
	v_cndmask_b32_e32 v106, v106, v118, vcc
	v_cndmask_b32_e32 v107, v107, v119, vcc
	v_mul_f32_e32 v104, v168, v104
	v_mul_f32_e32 v105, v168, v105
	v_cndmask_b32_e32 v108, v108, v120, vcc
	v_cndmask_b32_e32 v109, v109, v112, vcc
	v_cndmask_b32_e32 v110, v110, v113, vcc
	v_cndmask_b32_e32 v111, v111, v114, vcc
	v_mul_f32_e32 v106, v168, v106
	v_mul_f32_e32 v107, v168, v107
	v_cvt_pk_bf16_f32 v104, v104, v105
	v_cvt_pk_bf16_f32 v105, v106, v107
	v_mul_f32_e32 v108, v168, v108
	v_mul_f32_e32 v109, v168, v109
	v_mul_f32_e32 v110, v168, v110
	v_mul_f32_e32 v111, v168, v111
	global_store_dwordx2 v[150:151], v[104:105], off
	v_cvt_pk_bf16_f32 v104, v108, v109
	v_cvt_pk_bf16_f32 v105, v110, v111
	global_store_dwordx2 v[150:151], v[104:105], off offset:256
	s_nop 0
	ds_bpermute_b32 v113, v132, v96
	ds_bpermute_b32 v115, v132, v97
	ds_bpermute_b32 v124, v132, v102
	ds_bpermute_b32 v126, v132, v103
	ds_bpermute_b32 v117, v132, v98
	ds_bpermute_b32 v119, v132, v99
	ds_bpermute_b32 v121, v132, v100
	ds_bpermute_b32 v123, v132, v101
	s_waitcnt lgkmcnt(7)
	v_cndmask_b32_e64 v125, v113, -v113, s[6:7]
	s_waitcnt lgkmcnt(6)
	v_cndmask_b32_e64 v127, v115, -v115, s[6:7]
	s_waitcnt lgkmcnt(5)
	v_cndmask_b32_e64 v157, v124, -v124, s[6:7]
	s_waitcnt lgkmcnt(4)
	v_cndmask_b32_e64 v159, v126, -v126, s[6:7]
	s_waitcnt lgkmcnt(3)
	v_cndmask_b32_e64 v147, v117, -v117, s[6:7]
	s_waitcnt lgkmcnt(2)
	v_cndmask_b32_e64 v149, v119, -v119, s[6:7]
	s_waitcnt lgkmcnt(1)
	v_cndmask_b32_e64 v153, v121, -v121, s[6:7]
	s_waitcnt lgkmcnt(0)
	v_cndmask_b32_e64 v155, v123, -v123, s[6:7]
	v_mov_b32_e32 v113, v220
	v_mov_b32_e32 v124, v224
	v_mov_b32_e32 v126, v225
	v_mov_b32_e32 v117, v222
	v_mov_b32_e32 v146, v226
	v_mov_b32_e32 v119, v223
	v_mov_b32_e32 v148, v227
	v_mov_b32_e32 v152, v224
	v_mov_b32_e32 v154, v225
	v_mov_b32_e32 v156, v226
	v_mov_b32_e32 v158, v227
	v_mul_f32_e32 v108, v113, v125
	v_mul_f32_e32 v110, v221, v127
	v_mov_b32_e32 v121, v220
	v_mov_b32_e32 v123, v222
	v_mul_f32_e32 v112, v117, v147
	v_mul_f32_e32 v114, v119, v149
	v_fma_f32 v108, v96, v124, v108
	v_fma_f32 v109, v97, v126, v110
	v_mul_f32_e32 v116, v121, v153
	v_mul_f32_e32 v104, v221, v155
	v_mul_f32_e32 v118, v123, v157
	v_mul_f32_e32 v106, v223, v159
	v_fma_f32 v110, v98, v146, v112
	v_fma_f32 v111, v99, v148, v114
	v_cndmask_b32_e32 v96, v96, v108, vcc
	v_cndmask_b32_e32 v97, v97, v109, vcc
	v_fma_f32 v112, v100, v152, v116
	v_fma_f32 v104, v101, v154, v104
	v_fma_f32 v105, v102, v156, v118
	v_fma_f32 v106, v103, v158, v106
	v_cndmask_b32_e32 v98, v98, v110, vcc
	v_cndmask_b32_e32 v99, v99, v111, vcc
	v_mul_f32_e32 v96, v168, v96
	v_mul_f32_e32 v97, v168, v97
	v_cndmask_b32_e32 v100, v100, v112, vcc
	v_cndmask_b32_e32 v101, v101, v104, vcc
	v_cndmask_b32_e32 v102, v102, v105, vcc
	v_cndmask_b32_e32 v103, v103, v106, vcc
	v_mul_f32_e32 v98, v168, v98
	v_mul_f32_e32 v99, v168, v99
	v_cvt_pk_bf16_f32 v96, v96, v97
	v_cvt_pk_bf16_f32 v97, v98, v99
	v_mul_f32_e32 v100, v168, v100
	v_mul_f32_e32 v101, v168, v101
	v_mul_f32_e32 v102, v168, v102
	v_mul_f32_e32 v103, v168, v103
	global_store_dwordx2 v[150:151], v[96:97], off offset:8
	v_cvt_pk_bf16_f32 v96, v100, v101
	v_cvt_pk_bf16_f32 v97, v102, v103
	global_store_dwordx2 v[150:151], v[96:97], off offset:264
	v_add_u32_e32 v210, 128, v140
	v_lshlrev_b32_e32 v210, 6, v210
	v_and_b32_e32 v210, 0x3ffc0, v210
	global_load_dword v211, v[142:143], off offset:512
	global_load_dwordx4 v[212:215], v210, s[22:23] offset:32
	global_load_dwordx4 v[216:219], v210, s[22:23]
	global_load_dwordx4 v[220:223], v210, s[22:23] offset:48
	global_load_dwordx4 v[224:227], v210, s[22:23] offset:16
	v_add_u32_e32 v105, 32, v140
	v_lshlrev_b32_e32 v96, 6, v105
	v_and_b32_e32 v141, 0x3ffc0, v96
	ds_bpermute_b32 v109, v132, v88
	ds_bpermute_b32 v111, v132, v89
	ds_bpermute_b32 v118, v132, v92
	ds_bpermute_b32 v120, v132, v93
	ds_bpermute_b32 v113, v132, v90
	ds_bpermute_b32 v115, v132, v91
	ds_bpermute_b32 v122, v132, v94
	ds_bpermute_b32 v124, v132, v95
	v_mad_i64_i32 v[116:117], s[62:63], s60, v105, 0
	s_waitcnt lgkmcnt(7)
	v_cndmask_b32_e64 v119, v109, -v109, s[6:7]
	s_waitcnt lgkmcnt(6)
	v_cndmask_b32_e64 v121, v111, -v111, s[6:7]
	s_waitcnt lgkmcnt(5)
	v_cndmask_b32_e64 v127, v118, -v118, s[6:7]
	s_waitcnt lgkmcnt(4)
	v_cndmask_b32_e64 v147, v120, -v120, s[6:7]
	s_waitcnt lgkmcnt(3)
	v_cndmask_b32_e64 v123, v113, -v113, s[6:7]
	s_waitcnt lgkmcnt(2)
	v_cndmask_b32_e64 v125, v115, -v115, s[6:7]
	s_waitcnt lgkmcnt(1)
	v_cndmask_b32_e64 v149, v122, -v122, s[6:7]
	s_waitcnt lgkmcnt(0)
	v_cndmask_b32_e64 v151, v124, -v124, s[6:7]
	v_lshl_add_u64 v[116:117], v[116:117], 1, v[144:145]
	s_waitcnt vmcnt(18)
	v_mul_f32_e32 v152, s53, v229
	v_mov_b32_e32 v105, v230
	v_mov_b32_e32 v118, v234
	v_mov_b32_e32 v120, v235
	v_mov_b32_e32 v109, v232
	v_mov_b32_e32 v122, v236
	v_mov_b32_e32 v111, v233
	v_mov_b32_e32 v124, v237
	v_mov_b32_e32 v126, v234
	v_mov_b32_e32 v146, v235
	v_mov_b32_e32 v148, v236
	v_mov_b32_e32 v150, v237
	v_mul_f32_e32 v100, v105, v119
	v_mul_f32_e32 v102, v231, v121
	v_mov_b32_e32 v113, v230
	v_mov_b32_e32 v115, v232
	v_mul_f32_e32 v104, v109, v123
	v_mul_f32_e32 v106, v111, v125
	v_fma_f32 v100, v88, v118, v100
	v_fma_f32 v101, v89, v120, v102
	v_mul_f32_e32 v108, v113, v127
	v_mul_f32_e32 v96, v231, v147
	v_mul_f32_e32 v110, v115, v149
	v_mul_f32_e32 v98, v233, v151
	v_fma_f32 v102, v90, v122, v104
	v_fma_f32 v103, v91, v124, v106
	v_cndmask_b32_e32 v88, v88, v100, vcc
	v_cndmask_b32_e32 v89, v89, v101, vcc
	v_fma_f32 v104, v92, v126, v108
	v_fma_f32 v96, v93, v146, v96
	v_fma_f32 v97, v94, v148, v110
	v_fma_f32 v98, v95, v150, v98
	v_cndmask_b32_e32 v90, v90, v102, vcc
	v_cndmask_b32_e32 v91, v91, v103, vcc
	v_mul_f32_e32 v88, v152, v88
	v_mul_f32_e32 v89, v152, v89
	v_cndmask_b32_e32 v92, v92, v104, vcc
	v_cndmask_b32_e32 v93, v93, v96, vcc
	v_cndmask_b32_e32 v94, v94, v97, vcc
	v_cndmask_b32_e32 v95, v95, v98, vcc
	v_mul_f32_e32 v90, v152, v90
	v_mul_f32_e32 v91, v152, v91
	v_cvt_pk_bf16_f32 v88, v88, v89
	v_cvt_pk_bf16_f32 v89, v90, v91
	v_mul_f32_e32 v92, v152, v92
	v_mul_f32_e32 v93, v152, v93
	v_mul_f32_e32 v94, v152, v94
	v_mul_f32_e32 v95, v152, v95
	global_store_dwordx2 v[116:117], v[88:89], off
	v_cvt_pk_bf16_f32 v88, v92, v93
	v_cvt_pk_bf16_f32 v89, v94, v95
	global_store_dwordx2 v[116:117], v[88:89], off offset:256
	s_nop 0
	ds_bpermute_b32 v97, v132, v80
	ds_bpermute_b32 v99, v132, v81
	ds_bpermute_b32 v108, v132, v86
	ds_bpermute_b32 v110, v132, v87
	ds_bpermute_b32 v101, v132, v82
	ds_bpermute_b32 v103, v132, v83
	ds_bpermute_b32 v105, v132, v84
	ds_bpermute_b32 v107, v132, v85
	s_waitcnt lgkmcnt(7)
	v_cndmask_b32_e64 v109, v97, -v97, s[6:7]
	s_waitcnt lgkmcnt(6)
	v_cndmask_b32_e64 v111, v99, -v99, s[6:7]
	s_waitcnt lgkmcnt(5)
	v_cndmask_b32_e64 v123, v108, -v108, s[6:7]
	s_waitcnt lgkmcnt(4)
	v_cndmask_b32_e64 v125, v110, -v110, s[6:7]
	s_waitcnt lgkmcnt(3)
	v_cndmask_b32_e64 v113, v101, -v101, s[6:7]
	s_waitcnt lgkmcnt(2)
	v_cndmask_b32_e64 v115, v103, -v103, s[6:7]
	s_waitcnt lgkmcnt(1)
	v_cndmask_b32_e64 v119, v105, -v105, s[6:7]
	s_waitcnt lgkmcnt(0)
	v_cndmask_b32_e64 v121, v107, -v107, s[6:7]
	v_mov_b32_e32 v97, v238
	v_mov_b32_e32 v108, v242
	v_mov_b32_e32 v110, v243
	v_mov_b32_e32 v101, v240
	v_mov_b32_e32 v112, v244
	v_mov_b32_e32 v103, v241
	v_mov_b32_e32 v114, v245
	v_mov_b32_e32 v118, v242
	v_mov_b32_e32 v120, v243
	v_mov_b32_e32 v122, v244
	v_mov_b32_e32 v124, v245
	v_mul_f32_e32 v92, v97, v109
	v_mul_f32_e32 v94, v239, v111
	v_mov_b32_e32 v105, v238
	v_mov_b32_e32 v107, v240
	v_mul_f32_e32 v96, v101, v113
	v_mul_f32_e32 v98, v103, v115
	v_fma_f32 v92, v80, v108, v92
	v_fma_f32 v93, v81, v110, v94
	v_mul_f32_e32 v100, v105, v119
	v_mul_f32_e32 v88, v239, v121
	v_mul_f32_e32 v102, v107, v123
	v_mul_f32_e32 v90, v241, v125
	v_fma_f32 v94, v82, v112, v96
	v_fma_f32 v95, v83, v114, v98
	v_cndmask_b32_e32 v80, v80, v92, vcc
	v_cndmask_b32_e32 v81, v81, v93, vcc
	v_fma_f32 v96, v84, v118, v100
	v_fma_f32 v88, v85, v120, v88
	v_fma_f32 v89, v86, v122, v102
	v_fma_f32 v90, v87, v124, v90
	v_cndmask_b32_e32 v82, v82, v94, vcc
	v_cndmask_b32_e32 v83, v83, v95, vcc
	v_mul_f32_e32 v80, v152, v80
	v_mul_f32_e32 v81, v152, v81
	v_cndmask_b32_e32 v84, v84, v96, vcc
	v_cndmask_b32_e32 v85, v85, v88, vcc
	v_cndmask_b32_e32 v86, v86, v89, vcc
	v_cndmask_b32_e32 v87, v87, v90, vcc
	v_mul_f32_e32 v82, v152, v82
	v_mul_f32_e32 v83, v152, v83
	v_cvt_pk_bf16_f32 v80, v80, v81
	v_cvt_pk_bf16_f32 v81, v82, v83
	v_mul_f32_e32 v84, v152, v84
	v_mul_f32_e32 v85, v152, v85
	v_mul_f32_e32 v86, v152, v86
	v_mul_f32_e32 v87, v152, v87
	global_store_dwordx2 v[116:117], v[80:81], off offset:8
	v_cvt_pk_bf16_f32 v80, v84, v85
	v_cvt_pk_bf16_f32 v81, v86, v87
	global_store_dwordx2 v[116:117], v[80:81], off offset:264
	v_add_u32_e32 v228, 144, v140
	v_lshlrev_b32_e32 v228, 6, v228
	v_and_b32_e32 v228, 0x3ffc0, v228
	global_load_dword v229, v[142:143], off offset:576
	global_load_dwordx4 v[230:233], v228, s[22:23] offset:32
	global_load_dwordx4 v[234:237], v228, s[22:23]
	global_load_dwordx4 v[238:241], v228, s[22:23] offset:48
	global_load_dwordx4 v[242:245], v228, s[22:23] offset:16
	v_add_u32_e32 v89, 48, v140
	v_lshlrev_b32_e32 v80, 6, v89
	v_and_b32_e32 v118, 0x3ffc0, v80
	ds_bpermute_b32 v93, v132, v72
	ds_bpermute_b32 v95, v132, v73
	ds_bpermute_b32 v102, v132, v76
	ds_bpermute_b32 v104, v132, v77
	ds_bpermute_b32 v97, v132, v74
	ds_bpermute_b32 v99, v132, v75
	ds_bpermute_b32 v106, v132, v78
	ds_bpermute_b32 v108, v132, v79
	v_mad_i64_i32 v[100:101], s[62:63], s60, v89, 0
	s_waitcnt lgkmcnt(7)
	v_cndmask_b32_e64 v103, v93, -v93, s[6:7]
	s_waitcnt lgkmcnt(6)
	v_cndmask_b32_e64 v105, v95, -v95, s[6:7]
	s_waitcnt lgkmcnt(5)
	v_cndmask_b32_e64 v111, v102, -v102, s[6:7]
	s_waitcnt lgkmcnt(4)
	v_cndmask_b32_e64 v113, v104, -v104, s[6:7]
	s_waitcnt lgkmcnt(3)
	v_cndmask_b32_e64 v107, v97, -v97, s[6:7]
	s_waitcnt lgkmcnt(2)
	v_cndmask_b32_e64 v109, v99, -v99, s[6:7]
	s_waitcnt lgkmcnt(1)
	v_cndmask_b32_e64 v115, v106, -v106, s[6:7]
	s_waitcnt lgkmcnt(0)
	v_cndmask_b32_e64 v117, v108, -v108, s[6:7]
	v_lshl_add_u64 v[100:101], v[100:101], 1, v[144:145]
	s_waitcnt vmcnt(18)
	v_mul_f32_e32 v119, s53, v193
	v_mov_b32_e32 v89, v194
	v_mov_b32_e32 v102, v198
	v_mov_b32_e32 v104, v199
	v_mov_b32_e32 v93, v196
	v_mov_b32_e32 v106, v200
	v_mov_b32_e32 v95, v197
	v_mov_b32_e32 v108, v201
	v_mov_b32_e32 v110, v198
	v_mov_b32_e32 v112, v199
	v_mov_b32_e32 v114, v200
	v_mov_b32_e32 v116, v201
	v_mul_f32_e32 v84, v89, v103
	v_mul_f32_e32 v86, v195, v105
	v_mov_b32_e32 v97, v194
	v_mov_b32_e32 v99, v196
	v_mul_f32_e32 v88, v93, v107
	v_mul_f32_e32 v90, v95, v109
	v_fma_f32 v84, v72, v102, v84
	v_fma_f32 v85, v73, v104, v86
	v_mul_f32_e32 v92, v97, v111
	v_mul_f32_e32 v80, v195, v113
	v_mul_f32_e32 v94, v99, v115
	v_mul_f32_e32 v82, v197, v117
	v_fma_f32 v86, v74, v106, v88
	v_fma_f32 v87, v75, v108, v90
	v_cndmask_b32_e32 v72, v72, v84, vcc
	v_cndmask_b32_e32 v73, v73, v85, vcc
	v_fma_f32 v88, v76, v110, v92
	v_fma_f32 v80, v77, v112, v80
	v_fma_f32 v81, v78, v114, v94
	v_fma_f32 v82, v79, v116, v82
	v_cndmask_b32_e32 v74, v74, v86, vcc
	v_cndmask_b32_e32 v75, v75, v87, vcc
	v_mul_f32_e32 v72, v119, v72
	v_mul_f32_e32 v73, v119, v73
	v_cndmask_b32_e32 v76, v76, v88, vcc
	v_cndmask_b32_e32 v77, v77, v80, vcc
	v_cndmask_b32_e32 v78, v78, v81, vcc
	v_cndmask_b32_e32 v79, v79, v82, vcc
	v_mul_f32_e32 v74, v119, v74
	v_mul_f32_e32 v75, v119, v75
	v_cvt_pk_bf16_f32 v72, v72, v73
	v_cvt_pk_bf16_f32 v73, v74, v75
	v_mul_f32_e32 v76, v119, v76
	v_mul_f32_e32 v77, v119, v77
	v_mul_f32_e32 v78, v119, v78
	v_mul_f32_e32 v79, v119, v79
	global_store_dwordx2 v[100:101], v[72:73], off
	v_cvt_pk_bf16_f32 v72, v76, v77
	v_cvt_pk_bf16_f32 v73, v78, v79
	global_store_dwordx2 v[100:101], v[72:73], off offset:256
	s_nop 0
	ds_bpermute_b32 v81, v132, v64
	ds_bpermute_b32 v83, v132, v65
	ds_bpermute_b32 v92, v132, v70
	ds_bpermute_b32 v94, v132, v71
	ds_bpermute_b32 v85, v132, v66
	ds_bpermute_b32 v87, v132, v67
	ds_bpermute_b32 v89, v132, v68
	ds_bpermute_b32 v91, v132, v69
	s_waitcnt lgkmcnt(7)
	v_cndmask_b32_e64 v93, v81, -v81, s[6:7]
	s_waitcnt lgkmcnt(6)
	v_cndmask_b32_e64 v95, v83, -v83, s[6:7]
	s_waitcnt lgkmcnt(5)
	v_cndmask_b32_e64 v107, v92, -v92, s[6:7]
	s_waitcnt lgkmcnt(4)
	v_cndmask_b32_e64 v109, v94, -v94, s[6:7]
	s_waitcnt lgkmcnt(3)
	v_cndmask_b32_e64 v97, v85, -v85, s[6:7]
	s_waitcnt lgkmcnt(2)
	v_cndmask_b32_e64 v99, v87, -v87, s[6:7]
	s_waitcnt lgkmcnt(1)
	v_cndmask_b32_e64 v103, v89, -v89, s[6:7]
	s_waitcnt lgkmcnt(0)
	v_cndmask_b32_e64 v105, v91, -v91, s[6:7]
	v_mov_b32_e32 v81, v202
	v_mov_b32_e32 v92, v206
	v_mov_b32_e32 v94, v207
	v_mov_b32_e32 v85, v204
	v_mov_b32_e32 v96, v208
	v_mov_b32_e32 v87, v205
	v_mov_b32_e32 v98, v209
	v_mov_b32_e32 v102, v206
	v_mov_b32_e32 v104, v207
	v_mov_b32_e32 v106, v208
	v_mov_b32_e32 v108, v209
	v_mul_f32_e32 v76, v81, v93
	v_mul_f32_e32 v78, v203, v95
	v_mov_b32_e32 v89, v202
	v_mov_b32_e32 v91, v204
	v_mul_f32_e32 v80, v85, v97
	v_mul_f32_e32 v82, v87, v99
	v_fma_f32 v76, v64, v92, v76
	v_fma_f32 v77, v65, v94, v78
	v_mul_f32_e32 v84, v89, v103
	v_mul_f32_e32 v72, v203, v105
	v_mul_f32_e32 v86, v91, v107
	v_mul_f32_e32 v74, v205, v109
	v_fma_f32 v78, v66, v96, v80
	v_fma_f32 v79, v67, v98, v82
	v_cndmask_b32_e32 v64, v64, v76, vcc
	v_cndmask_b32_e32 v65, v65, v77, vcc
	v_fma_f32 v80, v68, v102, v84
	v_fma_f32 v72, v69, v104, v72
	v_fma_f32 v73, v70, v106, v86
	v_fma_f32 v74, v71, v108, v74
	v_cndmask_b32_e32 v66, v66, v78, vcc
	v_cndmask_b32_e32 v67, v67, v79, vcc
	v_mul_f32_e32 v64, v119, v64
	v_mul_f32_e32 v65, v119, v65
	v_cndmask_b32_e32 v68, v68, v80, vcc
	v_cndmask_b32_e32 v69, v69, v72, vcc
	v_cndmask_b32_e32 v70, v70, v73, vcc
	v_cndmask_b32_e32 v71, v71, v74, vcc
	v_mul_f32_e32 v66, v119, v66
	v_mul_f32_e32 v67, v119, v67
	v_cvt_pk_bf16_f32 v64, v64, v65
	v_cvt_pk_bf16_f32 v65, v66, v67
	v_mul_f32_e32 v68, v119, v68
	v_mul_f32_e32 v69, v119, v69
	v_mul_f32_e32 v70, v119, v70
	v_mul_f32_e32 v71, v119, v71
	global_store_dwordx2 v[100:101], v[64:65], off offset:8
	v_cvt_pk_bf16_f32 v64, v68, v69
	v_cvt_pk_bf16_f32 v65, v70, v71
	global_store_dwordx2 v[100:101], v[64:65], off offset:264
	v_add_u32_e32 v192, 160, v140
	v_lshlrev_b32_e32 v192, 6, v192
	v_and_b32_e32 v192, 0x3ffc0, v192
	global_load_dword v193, v[142:143], off offset:640
	global_load_dwordx4 v[194:197], v192, s[22:23] offset:32
	global_load_dwordx4 v[198:201], v192, s[22:23]
	global_load_dwordx4 v[202:205], v192, s[22:23] offset:48
	global_load_dwordx4 v[206:209], v192, s[22:23] offset:16
	v_add_u32_e32 v73, 0x80, v140
	v_lshlrev_b32_e32 v64, 6, v73
	v_and_b32_e32 v102, 0x3ffc0, v64
	ds_bpermute_b32 v77, v132, v56
	ds_bpermute_b32 v79, v132, v57
	ds_bpermute_b32 v86, v132, v60
	ds_bpermute_b32 v88, v132, v61
	ds_bpermute_b32 v81, v132, v58
	ds_bpermute_b32 v83, v132, v59
	ds_bpermute_b32 v90, v132, v62
	ds_bpermute_b32 v92, v132, v63
	v_mad_i64_i32 v[84:85], s[62:63], s60, v73, 0
	s_waitcnt lgkmcnt(7)
	v_cndmask_b32_e64 v87, v77, -v77, s[6:7]
	s_waitcnt lgkmcnt(6)
	v_cndmask_b32_e64 v89, v79, -v79, s[6:7]
	s_waitcnt lgkmcnt(5)
	v_cndmask_b32_e64 v95, v86, -v86, s[6:7]
	s_waitcnt lgkmcnt(4)
	v_cndmask_b32_e64 v97, v88, -v88, s[6:7]
	s_waitcnt lgkmcnt(3)
	v_cndmask_b32_e64 v91, v81, -v81, s[6:7]
	s_waitcnt lgkmcnt(2)
	v_cndmask_b32_e64 v93, v83, -v83, s[6:7]
	s_waitcnt lgkmcnt(1)
	v_cndmask_b32_e64 v99, v90, -v90, s[6:7]
	s_waitcnt lgkmcnt(0)
	v_cndmask_b32_e64 v101, v92, -v92, s[6:7]
	v_lshl_add_u64 v[84:85], v[84:85], 1, v[144:145]
	s_waitcnt vmcnt(18)
	v_mul_f32_e32 v103, s53, v211
	v_mov_b32_e32 v73, v212
	v_mov_b32_e32 v86, v216
	v_mov_b32_e32 v88, v217
	v_mov_b32_e32 v77, v214
	v_mov_b32_e32 v90, v218
	v_mov_b32_e32 v79, v215
	v_mov_b32_e32 v92, v219
	v_mov_b32_e32 v94, v216
	v_mov_b32_e32 v96, v217
	v_mov_b32_e32 v98, v218
	v_mov_b32_e32 v100, v219
	v_mul_f32_e32 v68, v73, v87
	v_mul_f32_e32 v70, v213, v89
	v_mov_b32_e32 v81, v212
	v_mov_b32_e32 v83, v214
	v_mul_f32_e32 v72, v77, v91
	v_mul_f32_e32 v74, v79, v93
	v_fma_f32 v68, v56, v86, v68
	v_fma_f32 v69, v57, v88, v70
	v_mul_f32_e32 v76, v81, v95
	v_mul_f32_e32 v64, v213, v97
	v_mul_f32_e32 v78, v83, v99
	v_mul_f32_e32 v66, v215, v101
	v_fma_f32 v70, v58, v90, v72
	v_fma_f32 v71, v59, v92, v74
	v_cndmask_b32_e32 v56, v56, v68, vcc
	v_cndmask_b32_e32 v57, v57, v69, vcc
	v_fma_f32 v72, v60, v94, v76
	v_fma_f32 v64, v61, v96, v64
	v_fma_f32 v65, v62, v98, v78
	v_fma_f32 v66, v63, v100, v66
	v_cndmask_b32_e32 v58, v58, v70, vcc
	v_cndmask_b32_e32 v59, v59, v71, vcc
	v_mul_f32_e32 v56, v103, v56
	v_mul_f32_e32 v57, v103, v57
	v_cndmask_b32_e32 v60, v60, v72, vcc
	v_cndmask_b32_e32 v61, v61, v64, vcc
	v_cndmask_b32_e32 v62, v62, v65, vcc
	v_cndmask_b32_e32 v63, v63, v66, vcc
	v_mul_f32_e32 v58, v103, v58
	v_mul_f32_e32 v59, v103, v59
	v_cvt_pk_bf16_f32 v56, v56, v57
	v_cvt_pk_bf16_f32 v57, v58, v59
	v_mul_f32_e32 v60, v103, v60
	v_mul_f32_e32 v61, v103, v61
	v_mul_f32_e32 v62, v103, v62
	v_mul_f32_e32 v63, v103, v63
	global_store_dwordx2 v[84:85], v[56:57], off
	v_cvt_pk_bf16_f32 v56, v60, v61
	v_cvt_pk_bf16_f32 v57, v62, v63
	global_store_dwordx2 v[84:85], v[56:57], off offset:256
	s_nop 0
	ds_bpermute_b32 v65, v132, v48
	ds_bpermute_b32 v67, v132, v49
	ds_bpermute_b32 v76, v132, v54
	ds_bpermute_b32 v78, v132, v55
	ds_bpermute_b32 v69, v132, v50
	ds_bpermute_b32 v71, v132, v51
	ds_bpermute_b32 v73, v132, v52
	ds_bpermute_b32 v75, v132, v53
	s_waitcnt lgkmcnt(7)
	v_cndmask_b32_e64 v77, v65, -v65, s[6:7]
	s_waitcnt lgkmcnt(6)
	v_cndmask_b32_e64 v79, v67, -v67, s[6:7]
	s_waitcnt lgkmcnt(5)
	v_cndmask_b32_e64 v91, v76, -v76, s[6:7]
	s_waitcnt lgkmcnt(4)
	v_cndmask_b32_e64 v93, v78, -v78, s[6:7]
	s_waitcnt lgkmcnt(3)
	v_cndmask_b32_e64 v81, v69, -v69, s[6:7]
	s_waitcnt lgkmcnt(2)
	v_cndmask_b32_e64 v83, v71, -v71, s[6:7]
	s_waitcnt lgkmcnt(1)
	v_cndmask_b32_e64 v87, v73, -v73, s[6:7]
	s_waitcnt lgkmcnt(0)
	v_cndmask_b32_e64 v89, v75, -v75, s[6:7]
	v_mov_b32_e32 v65, v220
	v_mov_b32_e32 v76, v224
	v_mov_b32_e32 v78, v225
	v_mov_b32_e32 v69, v222
	v_mov_b32_e32 v80, v226
	v_mov_b32_e32 v71, v223
	v_mov_b32_e32 v82, v227
	v_mov_b32_e32 v86, v224
	v_mov_b32_e32 v88, v225
	v_mov_b32_e32 v90, v226
	v_mov_b32_e32 v92, v227
	v_mul_f32_e32 v60, v65, v77
	v_mul_f32_e32 v62, v221, v79
	v_mov_b32_e32 v73, v220
	v_mov_b32_e32 v75, v222
	v_mul_f32_e32 v64, v69, v81
	v_mul_f32_e32 v66, v71, v83
	v_fma_f32 v60, v48, v76, v60
	v_fma_f32 v61, v49, v78, v62
	v_mul_f32_e32 v68, v73, v87
	v_mul_f32_e32 v56, v221, v89
	v_mul_f32_e32 v70, v75, v91
	v_mul_f32_e32 v58, v223, v93
	v_fma_f32 v62, v50, v80, v64
	v_fma_f32 v63, v51, v82, v66
	v_cndmask_b32_e32 v48, v48, v60, vcc
	v_cndmask_b32_e32 v49, v49, v61, vcc
	v_fma_f32 v64, v52, v86, v68
	v_fma_f32 v56, v53, v88, v56
	v_fma_f32 v57, v54, v90, v70
	v_fma_f32 v58, v55, v92, v58
	v_cndmask_b32_e32 v50, v50, v62, vcc
	v_cndmask_b32_e32 v51, v51, v63, vcc
	v_mul_f32_e32 v48, v103, v48
	v_mul_f32_e32 v49, v103, v49
	v_cndmask_b32_e32 v52, v52, v64, vcc
	v_cndmask_b32_e32 v53, v53, v56, vcc
	v_cndmask_b32_e32 v54, v54, v57, vcc
	v_cndmask_b32_e32 v55, v55, v58, vcc
	v_mul_f32_e32 v50, v103, v50
	v_mul_f32_e32 v51, v103, v51
	v_cvt_pk_bf16_f32 v48, v48, v49
	v_cvt_pk_bf16_f32 v49, v50, v51
	v_mul_f32_e32 v52, v103, v52
	v_mul_f32_e32 v53, v103, v53
	v_mul_f32_e32 v54, v103, v54
	v_mul_f32_e32 v55, v103, v55
	global_store_dwordx2 v[84:85], v[48:49], off offset:8
	v_cvt_pk_bf16_f32 v48, v52, v53
	v_cvt_pk_bf16_f32 v49, v54, v55
	global_store_dwordx2 v[84:85], v[48:49], off offset:264
	v_add_u32_e32 v210, 176, v140
	v_lshlrev_b32_e32 v210, 6, v210
	v_and_b32_e32 v210, 0x3ffc0, v210
	global_load_dword v211, v[142:143], off offset:704
	global_load_dwordx4 v[212:215], v210, s[22:23] offset:32
	global_load_dwordx4 v[216:219], v210, s[22:23]
	global_load_dwordx4 v[220:223], v210, s[22:23] offset:48
	global_load_dwordx4 v[224:227], v210, s[22:23] offset:16
	v_add_u32_e32 v57, 0x90, v140
	v_lshlrev_b32_e32 v48, 6, v57
	v_and_b32_e32 v86, 0x3ffc0, v48
	ds_bpermute_b32 v61, v132, v40
	ds_bpermute_b32 v63, v132, v41
	ds_bpermute_b32 v70, v132, v44
	ds_bpermute_b32 v72, v132, v45
	ds_bpermute_b32 v65, v132, v42
	ds_bpermute_b32 v67, v132, v43
	ds_bpermute_b32 v74, v132, v46
	ds_bpermute_b32 v76, v132, v47
	v_mad_i64_i32 v[68:69], s[62:63], s60, v57, 0
	s_waitcnt lgkmcnt(7)
	v_cndmask_b32_e64 v71, v61, -v61, s[6:7]
	s_waitcnt lgkmcnt(6)
	v_cndmask_b32_e64 v73, v63, -v63, s[6:7]
	s_waitcnt lgkmcnt(5)
	v_cndmask_b32_e64 v79, v70, -v70, s[6:7]
	s_waitcnt lgkmcnt(4)
	v_cndmask_b32_e64 v81, v72, -v72, s[6:7]
	s_waitcnt lgkmcnt(3)
	v_cndmask_b32_e64 v75, v65, -v65, s[6:7]
	s_waitcnt lgkmcnt(2)
	v_cndmask_b32_e64 v77, v67, -v67, s[6:7]
	s_waitcnt lgkmcnt(1)
	v_cndmask_b32_e64 v83, v74, -v74, s[6:7]
	s_waitcnt lgkmcnt(0)
	v_cndmask_b32_e64 v85, v76, -v76, s[6:7]
	v_lshl_add_u64 v[68:69], v[68:69], 1, v[144:145]
	s_waitcnt vmcnt(18)
	v_mul_f32_e32 v87, s53, v229
	v_mov_b32_e32 v57, v230
	v_mov_b32_e32 v70, v234
	v_mov_b32_e32 v72, v235
	v_mov_b32_e32 v61, v232
	v_mov_b32_e32 v74, v236
	v_mov_b32_e32 v63, v233
	v_mov_b32_e32 v76, v237
	v_mov_b32_e32 v78, v234
	v_mov_b32_e32 v80, v235
	v_mov_b32_e32 v82, v236
	v_mov_b32_e32 v84, v237
	v_mul_f32_e32 v52, v57, v71
	v_mul_f32_e32 v54, v231, v73
	v_mov_b32_e32 v65, v230
	v_mov_b32_e32 v67, v232
	v_mul_f32_e32 v56, v61, v75
	v_mul_f32_e32 v58, v63, v77
	v_fma_f32 v52, v40, v70, v52
	v_fma_f32 v53, v41, v72, v54
	v_mul_f32_e32 v60, v65, v79
	v_mul_f32_e32 v48, v231, v81
	v_mul_f32_e32 v62, v67, v83
	v_mul_f32_e32 v50, v233, v85
	v_fma_f32 v54, v42, v74, v56
	v_fma_f32 v55, v43, v76, v58
	v_cndmask_b32_e32 v40, v40, v52, vcc
	v_cndmask_b32_e32 v41, v41, v53, vcc
	v_fma_f32 v56, v44, v78, v60
	v_fma_f32 v48, v45, v80, v48
	v_fma_f32 v49, v46, v82, v62
	v_fma_f32 v50, v47, v84, v50
	v_cndmask_b32_e32 v42, v42, v54, vcc
	v_cndmask_b32_e32 v43, v43, v55, vcc
	v_mul_f32_e32 v40, v87, v40
	v_mul_f32_e32 v41, v87, v41
	v_cndmask_b32_e32 v44, v44, v56, vcc
	v_cndmask_b32_e32 v45, v45, v48, vcc
	v_cndmask_b32_e32 v46, v46, v49, vcc
	v_cndmask_b32_e32 v47, v47, v50, vcc
	v_mul_f32_e32 v42, v87, v42
	v_mul_f32_e32 v43, v87, v43
	v_cvt_pk_bf16_f32 v40, v40, v41
	v_cvt_pk_bf16_f32 v41, v42, v43
	v_mul_f32_e32 v44, v87, v44
	v_mul_f32_e32 v45, v87, v45
	v_mul_f32_e32 v46, v87, v46
	v_mul_f32_e32 v47, v87, v47
	global_store_dwordx2 v[68:69], v[40:41], off
	v_cvt_pk_bf16_f32 v40, v44, v45
	v_cvt_pk_bf16_f32 v41, v46, v47
	global_store_dwordx2 v[68:69], v[40:41], off offset:256
	s_nop 0
	ds_bpermute_b32 v49, v132, v32
	ds_bpermute_b32 v51, v132, v33
	ds_bpermute_b32 v60, v132, v38
	ds_bpermute_b32 v62, v132, v39
	ds_bpermute_b32 v53, v132, v34
	ds_bpermute_b32 v55, v132, v35
	ds_bpermute_b32 v57, v132, v36
	ds_bpermute_b32 v59, v132, v37
	s_waitcnt lgkmcnt(7)
	v_cndmask_b32_e64 v61, v49, -v49, s[6:7]
	s_waitcnt lgkmcnt(6)
	v_cndmask_b32_e64 v63, v51, -v51, s[6:7]
	s_waitcnt lgkmcnt(5)
	v_cndmask_b32_e64 v75, v60, -v60, s[6:7]
	s_waitcnt lgkmcnt(4)
	v_cndmask_b32_e64 v77, v62, -v62, s[6:7]
	s_waitcnt lgkmcnt(3)
	v_cndmask_b32_e64 v65, v53, -v53, s[6:7]
	s_waitcnt lgkmcnt(2)
	v_cndmask_b32_e64 v67, v55, -v55, s[6:7]
	s_waitcnt lgkmcnt(1)
	v_cndmask_b32_e64 v71, v57, -v57, s[6:7]
	s_waitcnt lgkmcnt(0)
	v_cndmask_b32_e64 v73, v59, -v59, s[6:7]
	v_mov_b32_e32 v49, v238
	v_mov_b32_e32 v60, v242
	v_mov_b32_e32 v62, v243
	v_mov_b32_e32 v53, v240
	v_mov_b32_e32 v64, v244
	v_mov_b32_e32 v55, v241
	v_mov_b32_e32 v66, v245
	v_mov_b32_e32 v70, v242
	v_mov_b32_e32 v72, v243
	v_mov_b32_e32 v74, v244
	v_mov_b32_e32 v76, v245
	v_mul_f32_e32 v44, v49, v61
	v_mul_f32_e32 v46, v239, v63
	v_mov_b32_e32 v57, v238
	v_mov_b32_e32 v59, v240
	v_mul_f32_e32 v48, v53, v65
	v_mul_f32_e32 v50, v55, v67
	v_fma_f32 v44, v32, v60, v44
	v_fma_f32 v45, v33, v62, v46
	v_mul_f32_e32 v52, v57, v71
	v_mul_f32_e32 v40, v239, v73
	v_mul_f32_e32 v54, v59, v75
	v_mul_f32_e32 v42, v241, v77
	v_fma_f32 v46, v34, v64, v48
	v_fma_f32 v47, v35, v66, v50
	v_cndmask_b32_e32 v32, v32, v44, vcc
	v_cndmask_b32_e32 v33, v33, v45, vcc
	v_fma_f32 v48, v36, v70, v52
	v_fma_f32 v40, v37, v72, v40
	v_fma_f32 v41, v38, v74, v54
	v_fma_f32 v42, v39, v76, v42
	v_cndmask_b32_e32 v34, v34, v46, vcc
	v_cndmask_b32_e32 v35, v35, v47, vcc
	v_mul_f32_e32 v32, v87, v32
	v_mul_f32_e32 v33, v87, v33
	v_cndmask_b32_e32 v36, v36, v48, vcc
	v_cndmask_b32_e32 v37, v37, v40, vcc
	v_cndmask_b32_e32 v38, v38, v41, vcc
	v_cndmask_b32_e32 v39, v39, v42, vcc
	v_mul_f32_e32 v34, v87, v34
	v_mul_f32_e32 v35, v87, v35
	v_cvt_pk_bf16_f32 v32, v32, v33
	v_cvt_pk_bf16_f32 v33, v34, v35
	v_mul_f32_e32 v36, v87, v36
	v_mul_f32_e32 v37, v87, v37
	v_mul_f32_e32 v38, v87, v38
	v_mul_f32_e32 v39, v87, v39
	global_store_dwordx2 v[68:69], v[32:33], off offset:8
	v_cvt_pk_bf16_f32 v32, v36, v37
	v_cvt_pk_bf16_f32 v33, v38, v39
	global_store_dwordx2 v[68:69], v[32:33], off offset:264
	v_add_u32_e32 v41, 0xa0, v140
	v_lshlrev_b32_e32 v32, 6, v41
	v_and_b32_e32 v70, 0x3ffc0, v32
	ds_bpermute_b32 v45, v132, v24
	ds_bpermute_b32 v47, v132, v25
	ds_bpermute_b32 v54, v132, v28
	ds_bpermute_b32 v56, v132, v29
	ds_bpermute_b32 v49, v132, v26
	ds_bpermute_b32 v51, v132, v27
	ds_bpermute_b32 v58, v132, v30
	ds_bpermute_b32 v60, v132, v31
	v_mad_i64_i32 v[52:53], s[62:63], s60, v41, 0
	s_waitcnt lgkmcnt(7)
	v_cndmask_b32_e64 v55, v45, -v45, s[6:7]
	s_waitcnt lgkmcnt(6)
	v_cndmask_b32_e64 v57, v47, -v47, s[6:7]
	s_waitcnt lgkmcnt(5)
	v_cndmask_b32_e64 v63, v54, -v54, s[6:7]
	s_waitcnt lgkmcnt(4)
	v_cndmask_b32_e64 v65, v56, -v56, s[6:7]
	s_waitcnt lgkmcnt(3)
	v_cndmask_b32_e64 v59, v49, -v49, s[6:7]
	s_waitcnt lgkmcnt(2)
	v_cndmask_b32_e64 v61, v51, -v51, s[6:7]
	s_waitcnt lgkmcnt(1)
	v_cndmask_b32_e64 v67, v58, -v58, s[6:7]
	s_waitcnt lgkmcnt(0)
	v_cndmask_b32_e64 v69, v60, -v60, s[6:7]
	v_lshl_add_u64 v[52:53], v[52:53], 1, v[144:145]
	s_waitcnt vmcnt(13)
	v_mul_f32_e32 v71, s53, v193
	v_mov_b32_e32 v41, v194
	v_mov_b32_e32 v54, v198
	v_mov_b32_e32 v56, v199
	v_mov_b32_e32 v45, v196
	v_mov_b32_e32 v58, v200
	v_mov_b32_e32 v47, v197
	v_mov_b32_e32 v60, v201
	v_mov_b32_e32 v62, v198
	v_mov_b32_e32 v64, v199
	v_mov_b32_e32 v66, v200
	v_mov_b32_e32 v68, v201
	v_mul_f32_e32 v36, v41, v55
	v_mul_f32_e32 v38, v195, v57
	v_mov_b32_e32 v49, v194
	v_mov_b32_e32 v51, v196
	v_mul_f32_e32 v40, v45, v59
	v_mul_f32_e32 v42, v47, v61
	v_fma_f32 v36, v24, v54, v36
	v_fma_f32 v37, v25, v56, v38
	v_mul_f32_e32 v44, v49, v63
	v_mul_f32_e32 v32, v195, v65
	v_mul_f32_e32 v46, v51, v67
	v_mul_f32_e32 v34, v197, v69
	v_fma_f32 v38, v26, v58, v40
	v_fma_f32 v39, v27, v60, v42
	v_cndmask_b32_e32 v24, v24, v36, vcc
	v_cndmask_b32_e32 v25, v25, v37, vcc
	v_fma_f32 v40, v28, v62, v44
	v_fma_f32 v32, v29, v64, v32
	v_fma_f32 v33, v30, v66, v46
	v_fma_f32 v34, v31, v68, v34
	v_cndmask_b32_e32 v26, v26, v38, vcc
	v_cndmask_b32_e32 v27, v27, v39, vcc
	v_mul_f32_e32 v24, v71, v24
	v_mul_f32_e32 v25, v71, v25
	v_cndmask_b32_e32 v28, v28, v40, vcc
	v_cndmask_b32_e32 v29, v29, v32, vcc
	v_cndmask_b32_e32 v30, v30, v33, vcc
	v_cndmask_b32_e32 v31, v31, v34, vcc
	v_mul_f32_e32 v26, v71, v26
	v_mul_f32_e32 v27, v71, v27
	v_cvt_pk_bf16_f32 v24, v24, v25
	v_cvt_pk_bf16_f32 v25, v26, v27
	v_mul_f32_e32 v28, v71, v28
	v_mul_f32_e32 v29, v71, v29
	v_mul_f32_e32 v30, v71, v30
	v_mul_f32_e32 v31, v71, v31
	global_store_dwordx2 v[52:53], v[24:25], off
	v_cvt_pk_bf16_f32 v24, v28, v29
	v_cvt_pk_bf16_f32 v25, v30, v31
	global_store_dwordx2 v[52:53], v[24:25], off offset:256
	s_nop 0
	ds_bpermute_b32 v33, v132, v16
	ds_bpermute_b32 v35, v132, v17
	ds_bpermute_b32 v44, v132, v22
	ds_bpermute_b32 v46, v132, v23
	ds_bpermute_b32 v37, v132, v18
	ds_bpermute_b32 v39, v132, v19
	ds_bpermute_b32 v41, v132, v20
	ds_bpermute_b32 v43, v132, v21
	s_waitcnt lgkmcnt(7)
	v_cndmask_b32_e64 v45, v33, -v33, s[6:7]
	s_waitcnt lgkmcnt(6)
	v_cndmask_b32_e64 v47, v35, -v35, s[6:7]
	s_waitcnt lgkmcnt(5)
	v_cndmask_b32_e64 v59, v44, -v44, s[6:7]
	s_waitcnt lgkmcnt(4)
	v_cndmask_b32_e64 v61, v46, -v46, s[6:7]
	s_waitcnt lgkmcnt(3)
	v_cndmask_b32_e64 v49, v37, -v37, s[6:7]
	s_waitcnt lgkmcnt(2)
	v_cndmask_b32_e64 v51, v39, -v39, s[6:7]
	s_waitcnt lgkmcnt(1)
	v_cndmask_b32_e64 v55, v41, -v41, s[6:7]
	s_waitcnt lgkmcnt(0)
	v_cndmask_b32_e64 v57, v43, -v43, s[6:7]
	v_mov_b32_e32 v33, v202
	v_mov_b32_e32 v44, v206
	v_mov_b32_e32 v46, v207
	v_mov_b32_e32 v37, v204
	v_mov_b32_e32 v48, v208
	v_mov_b32_e32 v39, v205
	v_mov_b32_e32 v50, v209
	v_mov_b32_e32 v54, v206
	v_mov_b32_e32 v56, v207
	v_mov_b32_e32 v58, v208
	v_mov_b32_e32 v60, v209
	v_mul_f32_e32 v28, v33, v45
	v_mul_f32_e32 v30, v203, v47
	v_mov_b32_e32 v41, v202
	v_mov_b32_e32 v43, v204
	v_mul_f32_e32 v32, v37, v49
	v_mul_f32_e32 v34, v39, v51
	v_fma_f32 v28, v16, v44, v28
	v_fma_f32 v29, v17, v46, v30
	v_mul_f32_e32 v36, v41, v55
	v_mul_f32_e32 v24, v203, v57
	v_mul_f32_e32 v38, v43, v59
	v_mul_f32_e32 v26, v205, v61
	v_fma_f32 v30, v18, v48, v32
	v_fma_f32 v31, v19, v50, v34
	v_cndmask_b32_e32 v16, v16, v28, vcc
	v_cndmask_b32_e32 v17, v17, v29, vcc
	v_fma_f32 v32, v20, v54, v36
	v_fma_f32 v24, v21, v56, v24
	v_fma_f32 v25, v22, v58, v38
	v_fma_f32 v26, v23, v60, v26
	v_cndmask_b32_e32 v18, v18, v30, vcc
	v_cndmask_b32_e32 v19, v19, v31, vcc
	v_mul_f32_e32 v16, v71, v16
	v_mul_f32_e32 v17, v71, v17
	v_cndmask_b32_e32 v20, v20, v32, vcc
	v_cndmask_b32_e32 v21, v21, v24, vcc
	v_cndmask_b32_e32 v22, v22, v25, vcc
	v_cndmask_b32_e32 v23, v23, v26, vcc
	v_mul_f32_e32 v18, v71, v18
	v_mul_f32_e32 v19, v71, v19
	v_cvt_pk_bf16_f32 v16, v16, v17
	v_cvt_pk_bf16_f32 v17, v18, v19
	v_mul_f32_e32 v20, v71, v20
	v_mul_f32_e32 v21, v71, v21
	v_mul_f32_e32 v22, v71, v22
	v_mul_f32_e32 v23, v71, v23
	global_store_dwordx2 v[52:53], v[16:17], off offset:8
	v_cvt_pk_bf16_f32 v16, v20, v21
	v_cvt_pk_bf16_f32 v17, v22, v23
	global_store_dwordx2 v[52:53], v[16:17], off offset:264
	v_add_u32_e32 v25, 0xb0, v140
	v_lshlrev_b32_e32 v16, 6, v25
	v_and_b32_e32 v54, 0x3ffc0, v16
	ds_bpermute_b32 v29, v132, v8
	ds_bpermute_b32 v31, v132, v9
	ds_bpermute_b32 v38, v132, v12
	ds_bpermute_b32 v40, v132, v13
	ds_bpermute_b32 v33, v132, v10
	ds_bpermute_b32 v35, v132, v11
	ds_bpermute_b32 v42, v132, v14
	ds_bpermute_b32 v44, v132, v15
	v_mad_i64_i32 v[36:37], s[60:61], s60, v25, 0
	s_waitcnt lgkmcnt(7)
	v_cndmask_b32_e64 v39, v29, -v29, s[6:7]
	s_waitcnt lgkmcnt(6)
	v_cndmask_b32_e64 v41, v31, -v31, s[6:7]
	s_waitcnt lgkmcnt(5)
	v_cndmask_b32_e64 v47, v38, -v38, s[6:7]
	s_waitcnt lgkmcnt(4)
	v_cndmask_b32_e64 v49, v40, -v40, s[6:7]
	s_waitcnt lgkmcnt(3)
	v_cndmask_b32_e64 v43, v33, -v33, s[6:7]
	s_waitcnt lgkmcnt(2)
	v_cndmask_b32_e64 v45, v35, -v35, s[6:7]
	s_waitcnt lgkmcnt(1)
	v_cndmask_b32_e64 v51, v42, -v42, s[6:7]
	s_waitcnt lgkmcnt(0)
	v_cndmask_b32_e64 v53, v44, -v44, s[6:7]
	v_lshl_add_u64 v[36:37], v[36:37], 1, v[144:145]
	s_waitcnt vmcnt(8)
	v_mul_f32_e32 v55, s53, v211
	v_mov_b32_e32 v25, v212
	v_mov_b32_e32 v38, v216
	v_mov_b32_e32 v40, v217
	v_mov_b32_e32 v29, v214
	v_mov_b32_e32 v42, v218
	v_mov_b32_e32 v31, v215
	v_mov_b32_e32 v44, v219
	v_mov_b32_e32 v46, v216
	v_mov_b32_e32 v48, v217
	v_mov_b32_e32 v50, v218
	v_mov_b32_e32 v52, v219
	v_mul_f32_e32 v20, v25, v39
	v_mul_f32_e32 v22, v213, v41
	v_mov_b32_e32 v33, v212
	v_mov_b32_e32 v35, v214
	v_mul_f32_e32 v24, v29, v43
	v_mul_f32_e32 v26, v31, v45
	v_fma_f32 v20, v8, v38, v20
	v_fma_f32 v21, v9, v40, v22
	v_mul_f32_e32 v28, v33, v47
	v_mul_f32_e32 v16, v213, v49
	v_mul_f32_e32 v30, v35, v51
	v_mul_f32_e32 v18, v215, v53
	v_fma_f32 v22, v10, v42, v24
	v_fma_f32 v23, v11, v44, v26
	v_cndmask_b32_e32 v8, v8, v20, vcc
	v_cndmask_b32_e32 v9, v9, v21, vcc
	v_fma_f32 v24, v12, v46, v28
	v_fma_f32 v16, v13, v48, v16
	v_fma_f32 v17, v14, v50, v30
	v_fma_f32 v18, v15, v52, v18
	v_cndmask_b32_e32 v10, v10, v22, vcc
	v_cndmask_b32_e32 v11, v11, v23, vcc
	v_mul_f32_e32 v8, v55, v8
	v_mul_f32_e32 v9, v55, v9
	v_cndmask_b32_e32 v12, v12, v24, vcc
	v_cndmask_b32_e32 v13, v13, v16, vcc
	v_cndmask_b32_e32 v14, v14, v17, vcc
	v_cndmask_b32_e32 v15, v15, v18, vcc
	v_mul_f32_e32 v10, v55, v10
	v_mul_f32_e32 v11, v55, v11
	v_cvt_pk_bf16_f32 v8, v8, v9
	v_cvt_pk_bf16_f32 v9, v10, v11
	v_mul_f32_e32 v12, v55, v12
	v_mul_f32_e32 v13, v55, v13
	v_mul_f32_e32 v14, v55, v14
	v_mul_f32_e32 v15, v55, v15
	global_store_dwordx2 v[36:37], v[8:9], off
	v_cvt_pk_bf16_f32 v8, v12, v13
	v_cvt_pk_bf16_f32 v9, v14, v15
	global_store_dwordx2 v[36:37], v[8:9], off offset:256
	s_nop 0
	ds_bpermute_b32 v17, v132, v0
	ds_bpermute_b32 v19, v132, v1
	ds_bpermute_b32 v28, v132, v6
	ds_bpermute_b32 v30, v132, v7
	ds_bpermute_b32 v21, v132, v2
	ds_bpermute_b32 v23, v132, v3
	ds_bpermute_b32 v25, v132, v4
	ds_bpermute_b32 v27, v132, v5
	s_waitcnt lgkmcnt(7)
	v_cndmask_b32_e64 v29, v17, -v17, s[6:7]
	s_waitcnt lgkmcnt(6)
	v_cndmask_b32_e64 v31, v19, -v19, s[6:7]
	s_waitcnt lgkmcnt(5)
	v_cndmask_b32_e64 v43, v28, -v28, s[6:7]
	s_waitcnt lgkmcnt(4)
	v_cndmask_b32_e64 v45, v30, -v30, s[6:7]
	s_waitcnt lgkmcnt(3)
	v_cndmask_b32_e64 v33, v21, -v21, s[6:7]
	s_waitcnt lgkmcnt(2)
	v_cndmask_b32_e64 v35, v23, -v23, s[6:7]
	v_mov_b32_e32 v24, v4
	v_mov_b32_e32 v26, v6
	s_waitcnt lgkmcnt(1)
	v_cndmask_b32_e64 v39, v25, -v25, s[6:7]
	s_waitcnt lgkmcnt(0)
	v_cndmask_b32_e64 v41, v27, -v27, s[6:7]
	v_mov_b32_e32 v17, v220
	v_mov_b32_e32 v28, v224
	v_mov_b32_e32 v19, v221
	v_mov_b32_e32 v30, v225
	v_mov_b32_e32 v21, v222
	v_mov_b32_e32 v32, v226
	v_mov_b32_e32 v23, v223
	v_mov_b32_e32 v34, v227
	v_mov_b32_e32 v38, v224
	v_mov_b32_e32 v40, v225
	v_mov_b32_e32 v42, v226
	v_mov_b32_e32 v44, v227
	v_mul_f32_e32 v12, v17, v29
	v_mul_f32_e32 v14, v221, v31
	v_mov_b32_e32 v25, v220
	v_mov_b32_e32 v27, v222
	v_mul_f32_e32 v16, v21, v33
	v_mul_f32_e32 v18, v23, v35
	v_fma_f32 v12, v0, v28, v12
	v_fma_f32 v13, v1, v30, v14
	v_mul_f32_e32 v20, v25, v39
	v_mul_f32_e32 v8, v221, v41
	v_mul_f32_e32 v22, v27, v43
	v_mul_f32_e32 v10, v223, v45
	v_fma_f32 v14, v2, v32, v16
	v_fma_f32 v15, v3, v34, v18
	v_cndmask_b32_e32 v0, v0, v12, vcc
	v_cndmask_b32_e32 v1, v1, v13, vcc
	v_fma_f32 v16, v4, v38, v20
	v_fma_f32 v8, v5, v40, v8
	v_fma_f32 v9, v6, v42, v22
	v_fma_f32 v10, v7, v44, v10
	v_cndmask_b32_e32 v2, v2, v14, vcc
	v_cndmask_b32_e32 v3, v3, v15, vcc
	v_mul_f32_e32 v0, v55, v0
	v_mul_f32_e32 v1, v55, v1
	v_cndmask_b32_e32 v4, v4, v16, vcc
	v_cndmask_b32_e32 v5, v5, v8, vcc
	v_cndmask_b32_e32 v6, v6, v9, vcc
	v_cndmask_b32_e32 v7, v7, v10, vcc
	v_mul_f32_e32 v2, v55, v2
	v_mul_f32_e32 v3, v55, v3
	v_cvt_pk_bf16_f32 v0, v0, v1
	v_cvt_pk_bf16_f32 v1, v2, v3
	v_mul_f32_e32 v4, v55, v4
	v_mul_f32_e32 v5, v55, v5
	v_mul_f32_e32 v6, v55, v6
	v_mul_f32_e32 v7, v55, v7
	global_store_dwordx2 v[36:37], v[0:1], off offset:8
	v_cvt_pk_bf16_f32 v0, v4, v5
	v_cvt_pk_bf16_f32 v1, v6, v7
	global_store_dwordx2 v[36:37], v[0:1], off offset:264
